# speedup vs baseline: 1.0080x; 1.0080x over previous
; #define GAS __attribute__((address_space(1)))
; __device__ __forceinline__ unsigned f2bf(float f) { return pk2(f, f) & 0xffffu; }
; __device__ __forceinline__ float sigmoidf_(float v) { return __builtin_amdgcn_rcpf(1.f + __builtin_amdgcn_exp2f(-LOG2E * v)); }
; __device__ __forceinline__ void phase_up(int pass) {
;     ...
;     EPI_IDS
;     const float* rr = (const float*)(smem_raw + LDS_RR) + par * 256;
;     GAS char* tb = (GAS char*)act + ((size_t)brow * FFP + (bcol >> 1)) * 2;
;     const unsigned off0 = (unsigned)((wr * 64 + fq * 4) * FFP + wc * 16 + fr) * 2u;
; #pragma unroll
;     for (int ai = 0; ai < 2; ++ai)
; #pragma unroll
;       for (int m = 0; m < 4; ++m)
; #pragma unroll
;         for (int j = 0; j < 4; ++j) {
;           const int rowl = ai * 128 + wr * 64 + m * 16 + fq * 4 + j;
;           const float r = rr[rowl];
; #pragma unroll
;           for (int bj = 0; bj < 2; ++bj) {
;             const float g = acc[ai][bj][m][0][j] * r, u = acc[ai][bj][m][1][j] * r;
;             const float v = g * sigmoidf_(g) * u;
;             *(GAS unsigned short*)(tb + (off0 + (unsigned)(((ai * 128 + m * 16 + j) * FFP + bj * 64) * 2))) = (unsigned short)f2bf(v);
;           }
;         }
.LBB0_85:
	v_ashrrev_i32_e32 v218, 2, v170
	v_and_b32_e32 v218, 0xffffffc0, v218
	v_lshrrev_b32_e32 v174, 2, v170
	v_and_b32_e32 v175, 12, v174
	v_or_b32_e32 v176, v218, v175
	v_and_b32_e32 v174, 48, v174
	v_and_b32_e32 v177, 15, v170
	v_mul_u32_u24_e32 v210, 0xb40, v176
	v_add3_u32 v210, v210, v174, v177
	v_lshlrev_b32_e32 v210, 1, v210
	v_add_u32_e32 v211, 0x1680, v210
	v_add_u32_e32 v212, 0x2d00, v210
	v_add_u32_e32 v213, 0x4380, v210
	s_lshl_b32 s18, s37, 10
	s_add_i32 s18, s18, 0x20100
	v_lshl_add_u32 v218, v176, 2, s18
	ds_read_b128 v[178:181], v218
	ds_read_b128 v[182:185], v218 offset:64
	ds_read_b128 v[186:189], v218 offset:128
	ds_read_b128 v[190:193], v218 offset:192
	ds_read_b128 v[194:197], v218 offset:512
	ds_read_b128 v[198:201], v218 offset:576
	ds_read_b128 v[202:205], v218 offset:640
	ds_read_b128 v[206:209], v218 offset:704
	v_mov_b32_e32 v214, 0xbfb8aa3b
	v_mov_b32_e32 v215, 0xbfb8aa3b
	v_mov_b32_e32 v216, 1.0
	v_mov_b32_e32 v217, 1.0
	s_lshl_b32 s19, s41, 7
	s_mul_hi_i32 s17, s16, 0xb40
	s_mulk_i32 s16, 0xb40
	s_ashr_i32 s20, s19, 31
	s_add_u32 s16, s16, s19
	s_addc_u32 s17, s17, s20
	s_lshl_b64 s[16:17], s[16:17], 1
	s_add_u32 s16, s35, s16
	s_addc_u32 s17, s36, s17
	s_waitcnt lgkmcnt(0)
	v_pk_mul_f32 v[118:119], v[118:119], v[178:179]
	v_pk_mul_f32 v[120:121], v[120:121], v[180:181]
	v_pk_mul_f32 v[174:175], v[214:215], v[118:119]
	v_pk_mul_f32 v[176:177], v[214:215], v[120:121]
	v_exp_f32_e32 v174, v174
	v_exp_f32_e32 v175, v175
	v_exp_f32_e32 v176, v176
	v_exp_f32_e32 v177, v177
	v_pk_mul_f32 v[114:115], v[114:115], v[178:179]
	v_pk_mul_f32 v[116:117], v[116:117], v[180:181]
	v_pk_add_f32 v[174:175], v[216:217], v[174:175]
	v_pk_add_f32 v[176:177], v[216:217], v[176:177]
	v_rcp_f32_e32 v174, v174
	v_rcp_f32_e32 v175, v175
	v_rcp_f32_e32 v176, v176
	v_rcp_f32_e32 v177, v177
	v_pk_mul_f32 v[118:119], v[118:119], v[174:175]
	v_pk_mul_f32 v[120:121], v[120:121], v[176:177]
	v_pk_mul_f32 v[114:115], v[114:115], v[118:119]
	v_pk_mul_f32 v[116:117], v[116:117], v[120:121]
	v_cvt_pk_bf16_f32 v114, v114, v115
	v_cvt_pk_bf16_f32 v115, v116, v117
	global_store_short v210, v114, s[16:17]
	global_store_short_d16_hi v211, v114, s[16:17]
	global_store_short v212, v115, s[16:17]
	global_store_short_d16_hi v213, v115, s[16:17]
	v_pk_mul_f32 v[126:127], v[126:127], v[178:179]
	v_pk_mul_f32 v[128:129], v[128:129], v[180:181]
	v_pk_mul_f32 v[174:175], v[214:215], v[126:127]
	v_pk_mul_f32 v[176:177], v[214:215], v[128:129]
	v_exp_f32_e32 v174, v174
	v_exp_f32_e32 v175, v175
	v_exp_f32_e32 v176, v176
	v_exp_f32_e32 v177, v177
	v_pk_mul_f32 v[122:123], v[122:123], v[178:179]
	v_pk_mul_f32 v[124:125], v[124:125], v[180:181]
	v_pk_add_f32 v[174:175], v[216:217], v[174:175]
	v_pk_add_f32 v[176:177], v[216:217], v[176:177]
	v_rcp_f32_e32 v174, v174
	v_rcp_f32_e32 v175, v175
	v_rcp_f32_e32 v176, v176
	v_rcp_f32_e32 v177, v177
	v_pk_mul_f32 v[126:127], v[126:127], v[174:175]
	v_pk_mul_f32 v[128:129], v[128:129], v[176:177]
	v_pk_mul_f32 v[122:123], v[122:123], v[126:127]
	v_pk_mul_f32 v[124:125], v[124:125], v[128:129]
	v_cvt_pk_bf16_f32 v122, v122, v123
	v_cvt_pk_bf16_f32 v123, v124, v125
	global_store_short v210, v122, s[16:17] offset:128
	global_store_short_d16_hi v211, v122, s[16:17] offset:128
	global_store_short v212, v123, s[16:17] offset:128
	global_store_short_d16_hi v213, v123, s[16:17] offset:128
	s_add_u32 s16, s16, 0x16800
	s_addc_u32 s17, s17, 0
	v_pk_mul_f32 v[102:103], v[102:103], v[182:183]
	v_pk_mul_f32 v[104:105], v[104:105], v[184:185]
	v_pk_mul_f32 v[174:175], v[214:215], v[102:103]
	v_pk_mul_f32 v[176:177], v[214:215], v[104:105]
	v_exp_f32_e32 v174, v174
	v_exp_f32_e32 v175, v175
	v_exp_f32_e32 v176, v176
	v_exp_f32_e32 v177, v177
	v_pk_mul_f32 v[98:99], v[98:99], v[182:183]
	v_pk_mul_f32 v[100:101], v[100:101], v[184:185]
	v_pk_add_f32 v[174:175], v[216:217], v[174:175]
	v_pk_add_f32 v[176:177], v[216:217], v[176:177]
	v_rcp_f32_e32 v174, v174
	v_rcp_f32_e32 v175, v175
	v_rcp_f32_e32 v176, v176
	v_rcp_f32_e32 v177, v177
	v_pk_mul_f32 v[102:103], v[102:103], v[174:175]
	v_pk_mul_f32 v[104:105], v[104:105], v[176:177]
	v_pk_mul_f32 v[98:99], v[98:99], v[102:103]
	v_pk_mul_f32 v[100:101], v[100:101], v[104:105]
	v_cvt_pk_bf16_f32 v98, v98, v99
	v_cvt_pk_bf16_f32 v99, v100, v101
	global_store_short v210, v98, s[16:17]
	global_store_short_d16_hi v211, v98, s[16:17]
	global_store_short v212, v99, s[16:17]
	global_store_short_d16_hi v213, v99, s[16:17]
	v_pk_mul_f32 v[110:111], v[110:111], v[182:183]
	v_pk_mul_f32 v[112:113], v[112:113], v[184:185]
	v_pk_mul_f32 v[174:175], v[214:215], v[110:111]
	v_pk_mul_f32 v[176:177], v[214:215], v[112:113]
	v_exp_f32_e32 v174, v174
	v_exp_f32_e32 v175, v175
	v_exp_f32_e32 v176, v176
	v_exp_f32_e32 v177, v177
	v_pk_mul_f32 v[106:107], v[106:107], v[182:183]
	v_pk_mul_f32 v[108:109], v[108:109], v[184:185]
	v_pk_add_f32 v[174:175], v[216:217], v[174:175]
	v_pk_add_f32 v[176:177], v[216:217], v[176:177]
	v_rcp_f32_e32 v174, v174
	v_rcp_f32_e32 v175, v175
	v_rcp_f32_e32 v176, v176
	v_rcp_f32_e32 v177, v177
	v_pk_mul_f32 v[110:111], v[110:111], v[174:175]
	v_pk_mul_f32 v[112:113], v[112:113], v[176:177]
	v_pk_mul_f32 v[106:107], v[106:107], v[110:111]
	v_pk_mul_f32 v[108:109], v[108:109], v[112:113]
	v_cvt_pk_bf16_f32 v106, v106, v107
	v_cvt_pk_bf16_f32 v107, v108, v109
	global_store_short v210, v106, s[16:17] offset:128
	global_store_short_d16_hi v211, v106, s[16:17] offset:128
	global_store_short v212, v107, s[16:17] offset:128
	global_store_short_d16_hi v213, v107, s[16:17] offset:128
	s_add_u32 s16, s16, 0x16800
; #define GAS __attribute__((address_space(1)))
; __device__ __forceinline__ unsigned f2bf(float f) { return pk2(f, f) & 0xffffu; }
; __device__ __forceinline__ float sigmoidf_(float v) { return __builtin_amdgcn_rcpf(1.f + __builtin_amdgcn_exp2f(-LOG2E * v)); }
; __device__ __forceinline__ void load_rr(const GAS float* ssq, int brow, int par) {
;     ...
;   if (tx < 256) {
;     const GAS f32x4* s = (const GAS f32x4*)(ssq + (size_t)(brow + tx) * 16);
;     f32x4 a = s[0], b = s[1], c = s[2], d = s[3];
;     float t = ((a.x + a.y) + (a.z + a.w)) + ((b.x + b.y) + (b.z + b.w)) + ((c.x + c.y) + (c.z + c.w)) + ((d.x + d.y) + (d.z + d.w));
;     rr[tx] = rsqrtf(t * (1.f / DM) + EPS);
;   }
; __device__ __forceinline__ void phase_up(int pass) {
;     ...
;         for (int j = 0; j < 4; ++j) {
;           const int rowl = ai * 128 + wr * 64 + m * 16 + fq * 4 + j;
;           const float r = rr[rowl];
; #pragma unroll
;           for (int bj = 0; bj < 2; ++bj) {
;             const float g = acc[ai][bj][m][0][j] * r, u = acc[ai][bj][m][1][j] * r;
;             const float v = g * sigmoidf_(g) * u;
;             *(GAS unsigned short*)(tb + (off0 + (unsigned)(((ai * 128 + m * 16 + j) * FFP + bj * 64) * 2))) = (unsigned short)f2bf(v);
;           }
;         }
	s_addc_u32 s17, s17, 0
	v_pk_mul_f32 v[86:87], v[86:87], v[186:187]
	v_pk_mul_f32 v[88:89], v[88:89], v[188:189]
	v_pk_mul_f32 v[174:175], v[214:215], v[86:87]
	v_pk_mul_f32 v[176:177], v[214:215], v[88:89]
	v_exp_f32_e32 v174, v174
	v_exp_f32_e32 v175, v175
	v_exp_f32_e32 v176, v176
	v_exp_f32_e32 v177, v177
	v_pk_mul_f32 v[82:83], v[82:83], v[186:187]
	v_pk_mul_f32 v[84:85], v[84:85], v[188:189]
	v_pk_add_f32 v[174:175], v[216:217], v[174:175]
	v_pk_add_f32 v[176:177], v[216:217], v[176:177]
	v_rcp_f32_e32 v174, v174
	v_rcp_f32_e32 v175, v175
	v_rcp_f32_e32 v176, v176
	v_rcp_f32_e32 v177, v177
	v_pk_mul_f32 v[86:87], v[86:87], v[174:175]
	v_pk_mul_f32 v[88:89], v[88:89], v[176:177]
	v_pk_mul_f32 v[82:83], v[82:83], v[86:87]
	v_pk_mul_f32 v[84:85], v[84:85], v[88:89]
	v_cvt_pk_bf16_f32 v82, v82, v83
	v_cvt_pk_bf16_f32 v83, v84, v85
	global_store_short v210, v82, s[16:17]
	global_store_short_d16_hi v211, v82, s[16:17]
	global_store_short v212, v83, s[16:17]
	global_store_short_d16_hi v213, v83, s[16:17]
	v_pk_mul_f32 v[94:95], v[94:95], v[186:187]
	v_pk_mul_f32 v[96:97], v[96:97], v[188:189]
	v_pk_mul_f32 v[174:175], v[214:215], v[94:95]
	v_pk_mul_f32 v[176:177], v[214:215], v[96:97]
	v_exp_f32_e32 v174, v174
	v_exp_f32_e32 v175, v175
	v_exp_f32_e32 v176, v176
	v_exp_f32_e32 v177, v177
	v_pk_mul_f32 v[90:91], v[90:91], v[186:187]
	v_pk_mul_f32 v[92:93], v[92:93], v[188:189]
	v_pk_add_f32 v[174:175], v[216:217], v[174:175]
	v_pk_add_f32 v[176:177], v[216:217], v[176:177]
	v_rcp_f32_e32 v174, v174
	v_rcp_f32_e32 v175, v175
	v_rcp_f32_e32 v176, v176
	v_rcp_f32_e32 v177, v177
	v_pk_mul_f32 v[94:95], v[94:95], v[174:175]
	v_pk_mul_f32 v[96:97], v[96:97], v[176:177]
	v_pk_mul_f32 v[90:91], v[90:91], v[94:95]
	v_pk_mul_f32 v[92:93], v[92:93], v[96:97]
	v_cvt_pk_bf16_f32 v90, v90, v91
	v_cvt_pk_bf16_f32 v91, v92, v93
	global_store_short v210, v90, s[16:17] offset:128
	global_store_short_d16_hi v211, v90, s[16:17] offset:128
	global_store_short v212, v91, s[16:17] offset:128
	global_store_short_d16_hi v213, v91, s[16:17] offset:128
	s_add_u32 s16, s16, 0x16800
	s_addc_u32 s17, s17, 0
	v_pk_mul_f32 v[70:71], v[70:71], v[190:191]
	v_pk_mul_f32 v[72:73], v[72:73], v[192:193]
	v_pk_mul_f32 v[174:175], v[214:215], v[70:71]
	v_pk_mul_f32 v[176:177], v[214:215], v[72:73]
	v_exp_f32_e32 v174, v174
	v_exp_f32_e32 v175, v175
	v_exp_f32_e32 v176, v176
	v_exp_f32_e32 v177, v177
	v_pk_mul_f32 v[66:67], v[66:67], v[190:191]
	v_pk_mul_f32 v[68:69], v[68:69], v[192:193]
	v_pk_add_f32 v[174:175], v[216:217], v[174:175]
	v_pk_add_f32 v[176:177], v[216:217], v[176:177]
	v_rcp_f32_e32 v174, v174
	v_rcp_f32_e32 v175, v175
	v_rcp_f32_e32 v176, v176
	v_rcp_f32_e32 v177, v177
	v_pk_mul_f32 v[70:71], v[70:71], v[174:175]
	v_pk_mul_f32 v[72:73], v[72:73], v[176:177]
	v_pk_mul_f32 v[66:67], v[66:67], v[70:71]
	v_pk_mul_f32 v[68:69], v[68:69], v[72:73]
	v_cvt_pk_bf16_f32 v66, v66, v67
	v_cvt_pk_bf16_f32 v67, v68, v69
	global_store_short v210, v66, s[16:17]
	global_store_short_d16_hi v211, v66, s[16:17]
	global_store_short v212, v67, s[16:17]
	global_store_short_d16_hi v213, v67, s[16:17]
	v_pk_mul_f32 v[78:79], v[78:79], v[190:191]
	v_pk_mul_f32 v[80:81], v[80:81], v[192:193]
	v_pk_mul_f32 v[174:175], v[214:215], v[78:79]
	v_pk_mul_f32 v[176:177], v[214:215], v[80:81]
	v_exp_f32_e32 v174, v174
	v_exp_f32_e32 v175, v175
	v_exp_f32_e32 v176, v176
	v_exp_f32_e32 v177, v177
	v_pk_mul_f32 v[74:75], v[74:75], v[190:191]
	v_pk_mul_f32 v[76:77], v[76:77], v[192:193]
	v_pk_add_f32 v[174:175], v[216:217], v[174:175]
	v_pk_add_f32 v[176:177], v[216:217], v[176:177]
	v_rcp_f32_e32 v174, v174
	v_rcp_f32_e32 v175, v175
	v_rcp_f32_e32 v176, v176
	v_rcp_f32_e32 v177, v177
	v_pk_mul_f32 v[78:79], v[78:79], v[174:175]
	v_pk_mul_f32 v[80:81], v[80:81], v[176:177]
	v_pk_mul_f32 v[74:75], v[74:75], v[78:79]
	v_pk_mul_f32 v[76:77], v[76:77], v[80:81]
	v_cvt_pk_bf16_f32 v74, v74, v75
	v_cvt_pk_bf16_f32 v75, v76, v77
	global_store_short v210, v74, s[16:17] offset:128
	global_store_short_d16_hi v211, v74, s[16:17] offset:128
	global_store_short v212, v75, s[16:17] offset:128
	global_store_short_d16_hi v213, v75, s[16:17] offset:128
	s_and_b64 vcc, exec, s[14:15]
	s_cbranch_vccnz .Lup0_rr_skip
	v_cmp_gt_i32_e32 vcc, s34, v170
	s_and_saveexec_b64 s[20:21], vcc
	s_cbranch_execz .Lup0_rr_done
	s_lshl_b32 s19, s37, 10
	s_xor_b32 s19, s19, 0x400
	s_addk_i32 s19, 0x100
	v_lshl_add_u32 v130, v170, 2, s19
	v_add_u32_e32 v130, 0x20000, v130
	s_waitcnt vmcnt(32)
	v_mov_b32_e32 v132, v137
	v_mov_b32_e32 v133, v138
	v_mov_b32_e32 v137, v139
	v_mov_b32_e32 v138, v141
	v_mov_b32_e32 v139, v142
	v_mov_b32_e32 v141, v143
	v_pk_add_f32 v[132:133], v[132:133], v[136:137]
	v_pk_add_f32 v[136:137], v[138:139], v[140:141]
	v_pk_add_f32 v[132:133], v[132:133], v[132:133] op_sel:[0,1] op_sel_hi:[1,0]
	v_pk_add_f32 v[136:137], v[136:137], v[136:137] op_sel:[0,1] op_sel_hi:[1,0]
	v_add_f32_e32 v142, v144, v145
	v_add_f32_e32 v144, v146, v147
	v_mov_b32_e32 v143, v150
	v_mov_b32_e32 v145, v151
	v_mov_b32_e32 v133, v148
	v_mov_b32_e32 v137, v149
	v_pk_add_f32 v[138:139], v[142:143], v[144:145]
	v_pk_add_f32 v[132:133], v[132:133], v[136:137]
	s_nop 0
	v_pk_add_f32 v[132:133], v[132:133], v[138:139]
	s_nop 0
	v_add_f32_e32 v132, v132, v133
	v_fmamk_f32 v132, v132, 0x3a800000, v135
	v_mul_f32_e32 v133, 0x4b800000, v132
	v_cmp_gt_f32_e32 vcc, s39, v132
	s_nop 1
	v_cndmask_b32_e32 v132, v132, v133, vcc
	v_rsq_f32_e32 v132, v132
	s_nop 0
	v_mul_f32_e32 v133, 0x45800000, v132
	v_cndmask_b32_e32 v132, v132, v133, vcc
	ds_write_b32 v130, v132

; #define GAS __attribute__((address_space(1)))
; __device__ __forceinline__ unsigned f2bf(float f) { return pk2(f, f) & 0xffffu; }
; __device__ __forceinline__ float sigmoidf_(float v) { return __builtin_amdgcn_rcpf(1.f + __builtin_amdgcn_exp2f(-LOG2E * v)); }
; __device__ __forceinline__ void phase_up(int pass) {
;     ...
;         for (int j = 0; j < 4; ++j) {
;           const int rowl = ai * 128 + wr * 64 + m * 16 + fq * 4 + j;
;           const float r = rr[rowl];
; #pragma unroll
;           for (int bj = 0; bj < 2; ++bj) {
;             const float g = acc[ai][bj][m][0][j] * r, u = acc[ai][bj][m][1][j] * r;
;             const float v = g * sigmoidf_(g) * u;
;             *(GAS unsigned short*)(tb + (off0 + (unsigned)(((ai * 128 + m * 16 + j) * FFP + bj * 64) * 2))) = (unsigned short)f2bf(v);
;           }
;         }
.Lup0_rr_skip:
	s_add_u32 s16, s16, 0x70800
	s_addc_u32 s17, s17, 0
	v_pk_mul_f32 v[54:55], v[54:55], v[194:195]
	v_pk_mul_f32 v[56:57], v[56:57], v[196:197]
	v_pk_mul_f32 v[174:175], v[214:215], v[54:55]
	v_pk_mul_f32 v[176:177], v[214:215], v[56:57]
	v_exp_f32_e32 v174, v174
	v_exp_f32_e32 v175, v175
	v_exp_f32_e32 v176, v176
	v_exp_f32_e32 v177, v177
	v_pk_mul_f32 v[50:51], v[50:51], v[194:195]
	v_pk_mul_f32 v[52:53], v[52:53], v[196:197]
	v_pk_add_f32 v[174:175], v[216:217], v[174:175]
	v_pk_add_f32 v[176:177], v[216:217], v[176:177]
	v_rcp_f32_e32 v174, v174
	v_rcp_f32_e32 v175, v175
	v_rcp_f32_e32 v176, v176
	v_rcp_f32_e32 v177, v177
	v_pk_mul_f32 v[54:55], v[54:55], v[174:175]
	v_pk_mul_f32 v[56:57], v[56:57], v[176:177]
	v_pk_mul_f32 v[50:51], v[50:51], v[54:55]
	v_pk_mul_f32 v[52:53], v[52:53], v[56:57]
	v_cvt_pk_bf16_f32 v50, v50, v51
	v_cvt_pk_bf16_f32 v51, v52, v53
	global_store_short v210, v50, s[16:17]
	global_store_short_d16_hi v211, v50, s[16:17]
	global_store_short v212, v51, s[16:17]
	global_store_short_d16_hi v213, v51, s[16:17]
	v_pk_mul_f32 v[62:63], v[62:63], v[194:195]
	v_pk_mul_f32 v[64:65], v[64:65], v[196:197]
	v_pk_mul_f32 v[174:175], v[214:215], v[62:63]
	v_pk_mul_f32 v[176:177], v[214:215], v[64:65]
	v_exp_f32_e32 v174, v174
	v_exp_f32_e32 v175, v175
	v_exp_f32_e32 v176, v176
	v_exp_f32_e32 v177, v177
	v_pk_mul_f32 v[58:59], v[58:59], v[194:195]
	v_pk_mul_f32 v[60:61], v[60:61], v[196:197]
	v_pk_add_f32 v[174:175], v[216:217], v[174:175]
	v_pk_add_f32 v[176:177], v[216:217], v[176:177]
	v_rcp_f32_e32 v174, v174
	v_rcp_f32_e32 v175, v175
	v_rcp_f32_e32 v176, v176
	v_rcp_f32_e32 v177, v177
	v_pk_mul_f32 v[62:63], v[62:63], v[174:175]
	v_pk_mul_f32 v[64:65], v[64:65], v[176:177]
	v_pk_mul_f32 v[58:59], v[58:59], v[62:63]
	v_pk_mul_f32 v[60:61], v[60:61], v[64:65]
	v_cvt_pk_bf16_f32 v58, v58, v59
	v_cvt_pk_bf16_f32 v59, v60, v61
	global_store_short v210, v58, s[16:17] offset:128
	global_store_short_d16_hi v211, v58, s[16:17] offset:128
	global_store_short v212, v59, s[16:17] offset:128
	global_store_short_d16_hi v213, v59, s[16:17] offset:128
	s_add_u32 s16, s16, 0x16800
	s_addc_u32 s17, s17, 0
	v_pk_mul_f32 v[42:43], v[42:43], v[198:199]
	v_pk_mul_f32 v[44:45], v[44:45], v[200:201]
	v_pk_mul_f32 v[174:175], v[214:215], v[42:43]
	v_pk_mul_f32 v[176:177], v[214:215], v[44:45]
	v_exp_f32_e32 v174, v174
	v_exp_f32_e32 v175, v175
	v_exp_f32_e32 v176, v176
	v_exp_f32_e32 v177, v177
	v_pk_mul_f32 v[34:35], v[34:35], v[198:199]
	v_pk_mul_f32 v[36:37], v[36:37], v[200:201]
	v_pk_add_f32 v[174:175], v[216:217], v[174:175]
	v_pk_add_f32 v[176:177], v[216:217], v[176:177]
	v_rcp_f32_e32 v174, v174
	v_rcp_f32_e32 v175, v175
	v_rcp_f32_e32 v176, v176
	v_rcp_f32_e32 v177, v177
	v_pk_mul_f32 v[42:43], v[42:43], v[174:175]
	v_pk_mul_f32 v[44:45], v[44:45], v[176:177]
	v_pk_mul_f32 v[34:35], v[34:35], v[42:43]
	v_pk_mul_f32 v[36:37], v[36:37], v[44:45]
	v_cvt_pk_bf16_f32 v34, v34, v35
	v_cvt_pk_bf16_f32 v35, v36, v37
	global_store_short v210, v34, s[16:17]
	global_store_short_d16_hi v211, v34, s[16:17]
	global_store_short v212, v35, s[16:17]
	global_store_short_d16_hi v213, v35, s[16:17]
	v_pk_mul_f32 v[46:47], v[46:47], v[198:199]
	v_pk_mul_f32 v[48:49], v[48:49], v[200:201]
	v_pk_mul_f32 v[174:175], v[214:215], v[46:47]
	v_pk_mul_f32 v[176:177], v[214:215], v[48:49]
	v_exp_f32_e32 v174, v174
	v_exp_f32_e32 v175, v175
	v_exp_f32_e32 v176, v176
	v_exp_f32_e32 v177, v177
	v_pk_mul_f32 v[38:39], v[38:39], v[198:199]
	v_pk_mul_f32 v[40:41], v[40:41], v[200:201]
	v_pk_add_f32 v[174:175], v[216:217], v[174:175]
	v_pk_add_f32 v[176:177], v[216:217], v[176:177]
	v_rcp_f32_e32 v174, v174
	v_rcp_f32_e32 v175, v175
	v_rcp_f32_e32 v176, v176
	v_rcp_f32_e32 v177, v177
	v_pk_mul_f32 v[46:47], v[46:47], v[174:175]
	v_pk_mul_f32 v[48:49], v[48:49], v[176:177]
	v_pk_mul_f32 v[38:39], v[38:39], v[46:47]
	v_pk_mul_f32 v[40:41], v[40:41], v[48:49]
	v_cvt_pk_bf16_f32 v38, v38, v39
	v_cvt_pk_bf16_f32 v39, v40, v41
	global_store_short v210, v38, s[16:17] offset:128
	global_store_short_d16_hi v211, v38, s[16:17] offset:128
	global_store_short v212, v39, s[16:17] offset:128
	global_store_short_d16_hi v213, v39, s[16:17] offset:128
	s_add_u32 s16, s16, 0x16800
; #define GAS __attribute__((address_space(1)))
; __device__ __forceinline__ unsigned f2bf(float f) { return pk2(f, f) & 0xffffu; }
; __device__ __forceinline__ float sigmoidf_(float v) { return __builtin_amdgcn_rcpf(1.f + __builtin_amdgcn_exp2f(-LOG2E * v)); }
; __device__ __forceinline__ void phase_up(int pass) {
;     ...
;         for (int j = 0; j < 4; ++j) {
;           const int rowl = ai * 128 + wr * 64 + m * 16 + fq * 4 + j;
;           const float r = rr[rowl];
; #pragma unroll
;           for (int bj = 0; bj < 2; ++bj) {
;             const float g = acc[ai][bj][m][0][j] * r, u = acc[ai][bj][m][1][j] * r;
;             const float v = g * sigmoidf_(g) * u;
;             *(GAS unsigned short*)(tb + (off0 + (unsigned)(((ai * 128 + m * 16 + j) * FFP + bj * 64) * 2))) = (unsigned short)f2bf(v);
;           }
;         }
;     par ^= 1;
	s_addc_u32 s17, s17, 0
	v_pk_mul_f32 v[22:23], v[22:23], v[202:203]
	v_pk_mul_f32 v[24:25], v[24:25], v[204:205]
	v_pk_mul_f32 v[174:175], v[214:215], v[22:23]
	v_pk_mul_f32 v[176:177], v[214:215], v[24:25]
	v_exp_f32_e32 v174, v174
	v_exp_f32_e32 v175, v175
	v_exp_f32_e32 v176, v176
	v_exp_f32_e32 v177, v177
	v_pk_mul_f32 v[18:19], v[18:19], v[202:203]
	v_pk_mul_f32 v[20:21], v[20:21], v[204:205]
	v_pk_add_f32 v[174:175], v[216:217], v[174:175]
	v_pk_add_f32 v[176:177], v[216:217], v[176:177]
	v_rcp_f32_e32 v174, v174
	v_rcp_f32_e32 v175, v175
	v_rcp_f32_e32 v176, v176
	v_rcp_f32_e32 v177, v177
	v_pk_mul_f32 v[22:23], v[22:23], v[174:175]
	v_pk_mul_f32 v[24:25], v[24:25], v[176:177]
	v_pk_mul_f32 v[18:19], v[18:19], v[22:23]
	v_pk_mul_f32 v[20:21], v[20:21], v[24:25]
	v_cvt_pk_bf16_f32 v18, v18, v19
	v_cvt_pk_bf16_f32 v19, v20, v21
	global_store_short v210, v18, s[16:17]
	global_store_short_d16_hi v211, v18, s[16:17]
	global_store_short v212, v19, s[16:17]
	global_store_short_d16_hi v213, v19, s[16:17]
	v_pk_mul_f32 v[30:31], v[30:31], v[202:203]
	v_pk_mul_f32 v[32:33], v[32:33], v[204:205]
	v_pk_mul_f32 v[174:175], v[214:215], v[30:31]
	v_pk_mul_f32 v[176:177], v[214:215], v[32:33]
	v_exp_f32_e32 v174, v174
	v_exp_f32_e32 v175, v175
	v_exp_f32_e32 v176, v176
	v_exp_f32_e32 v177, v177
	v_pk_mul_f32 v[26:27], v[26:27], v[202:203]
	v_pk_mul_f32 v[28:29], v[28:29], v[204:205]
	v_pk_add_f32 v[174:175], v[216:217], v[174:175]
	v_pk_add_f32 v[176:177], v[216:217], v[176:177]
	v_rcp_f32_e32 v174, v174
	v_rcp_f32_e32 v175, v175
	v_rcp_f32_e32 v176, v176
	v_rcp_f32_e32 v177, v177
	v_pk_mul_f32 v[30:31], v[30:31], v[174:175]
	v_pk_mul_f32 v[32:33], v[32:33], v[176:177]
	v_pk_mul_f32 v[26:27], v[26:27], v[30:31]
	v_pk_mul_f32 v[28:29], v[28:29], v[32:33]
	v_cvt_pk_bf16_f32 v26, v26, v27
	v_cvt_pk_bf16_f32 v27, v28, v29
	global_store_short v210, v26, s[16:17] offset:128
	global_store_short_d16_hi v211, v26, s[16:17] offset:128
	global_store_short v212, v27, s[16:17] offset:128
	global_store_short_d16_hi v213, v27, s[16:17] offset:128
	s_add_u32 s16, s16, 0x16800
	s_addc_u32 s17, s17, 0
	v_pk_mul_f32 v[10:11], v[10:11], v[206:207]
	v_pk_mul_f32 v[12:13], v[12:13], v[208:209]
	v_pk_mul_f32 v[174:175], v[214:215], v[10:11]
	v_pk_mul_f32 v[176:177], v[214:215], v[12:13]
	v_exp_f32_e32 v174, v174
	v_exp_f32_e32 v175, v175
	v_exp_f32_e32 v176, v176
	v_exp_f32_e32 v177, v177
	v_pk_mul_f32 v[2:3], v[2:3], v[206:207]
	v_pk_mul_f32 v[4:5], v[4:5], v[208:209]
	v_pk_add_f32 v[174:175], v[216:217], v[174:175]
	v_pk_add_f32 v[176:177], v[216:217], v[176:177]
	v_rcp_f32_e32 v174, v174
	v_rcp_f32_e32 v175, v175
	v_rcp_f32_e32 v176, v176
	v_rcp_f32_e32 v177, v177
	v_pk_mul_f32 v[10:11], v[10:11], v[174:175]
	v_pk_mul_f32 v[12:13], v[12:13], v[176:177]
	v_pk_mul_f32 v[2:3], v[2:3], v[10:11]
	v_pk_mul_f32 v[4:5], v[4:5], v[12:13]
	v_cvt_pk_bf16_f32 v2, v2, v3
	v_cvt_pk_bf16_f32 v3, v4, v5
	global_store_short v210, v2, s[16:17]
	global_store_short_d16_hi v211, v2, s[16:17]
	global_store_short v212, v3, s[16:17]
	global_store_short_d16_hi v213, v3, s[16:17]
	v_pk_mul_f32 v[14:15], v[14:15], v[206:207]
	v_pk_mul_f32 v[16:17], v[16:17], v[208:209]
	v_pk_mul_f32 v[174:175], v[214:215], v[14:15]
	v_pk_mul_f32 v[176:177], v[214:215], v[16:17]
	v_exp_f32_e32 v174, v174
	v_exp_f32_e32 v175, v175
	v_exp_f32_e32 v176, v176
	v_exp_f32_e32 v177, v177
	v_pk_mul_f32 v[6:7], v[6:7], v[206:207]
	v_pk_mul_f32 v[8:9], v[8:9], v[208:209]
	v_pk_add_f32 v[174:175], v[216:217], v[174:175]
	v_pk_add_f32 v[176:177], v[216:217], v[176:177]
	v_rcp_f32_e32 v174, v174
	v_rcp_f32_e32 v175, v175
	v_rcp_f32_e32 v176, v176
	v_rcp_f32_e32 v177, v177
	v_pk_mul_f32 v[14:15], v[14:15], v[174:175]
	v_pk_mul_f32 v[16:17], v[16:17], v[176:177]
	v_pk_mul_f32 v[6:7], v[6:7], v[14:15]
	v_pk_mul_f32 v[8:9], v[8:9], v[16:17]
	v_cvt_pk_bf16_f32 v6, v6, v7
	v_cvt_pk_bf16_f32 v7, v8, v9
	global_store_short v210, v6, s[16:17] offset:128
	global_store_short_d16_hi v211, v6, s[16:17] offset:128
	global_store_short v212, v7, s[16:17] offset:128
	global_store_short_d16_hi v213, v7, s[16:17] offset:128
	s_xor_b32 s37, s37, 1
	s_andn2_b64 vcc, exec, s[14:15]
	s_mov_b32 s41, s22
	s_cbranch_vccz .LBB0_95

; #define GAS __attribute__((address_space(1)))
; __device__ __forceinline__ unsigned f2bf(float f) { return pk2(f, f) & 0xffffu; }
; __device__ __forceinline__ float sigmoidf_(float v) { return __builtin_amdgcn_rcpf(1.f + __builtin_amdgcn_exp2f(-LOG2E * v)); }
; __device__ __forceinline__ void phase_up(int pass) {
;     ...
;     EPI_IDS
;     const float* rr = (const float*)(smem_raw + LDS_RR) + par * 256;
;     GAS char* tb = (GAS char*)act + ((size_t)brow * FFP + (bcol >> 1)) * 2;
;     const unsigned off0 = (unsigned)((wr * 64 + fq * 4) * FFP + wc * 16 + fr) * 2u;
; #pragma unroll
;     for (int ai = 0; ai < 2; ++ai)
; #pragma unroll
;       for (int m = 0; m < 4; ++m)
; #pragma unroll
;         for (int j = 0; j < 4; ++j) {
;           const int rowl = ai * 128 + wr * 64 + m * 16 + fq * 4 + j;
;           const float r = rr[rowl];
; #pragma unroll
;           for (int bj = 0; bj < 2; ++bj) {
;             const float g = acc[ai][bj][m][0][j] * r, u = acc[ai][bj][m][1][j] * r;
;             const float v = g * sigmoidf_(g) * u;
;             *(GAS unsigned short*)(tb + (off0 + (unsigned)(((ai * 128 + m * 16 + j) * FFP + bj * 64) * 2))) = (unsigned short)f2bf(v);
;           }
;         }
.LBB0_880:
	v_ashrrev_i32_e32 v218, 2, v170
	v_and_b32_e32 v218, 0xffffffc0, v218
	v_lshrrev_b32_e32 v174, 2, v170
	v_and_b32_e32 v175, 12, v174
	v_or_b32_e32 v176, v218, v175
	v_and_b32_e32 v174, 48, v174
	v_and_b32_e32 v177, 15, v170
	v_mul_u32_u24_e32 v210, 0xb40, v176
	v_add3_u32 v210, v210, v174, v177
	v_lshlrev_b32_e32 v210, 1, v210
	v_add_u32_e32 v211, 0x1680, v210
	v_add_u32_e32 v212, 0x2d00, v210
	v_add_u32_e32 v213, 0x4380, v210
	s_lshl_b32 s16, s37, 10
	s_add_i32 s16, s16, 0x20100
	v_lshl_add_u32 v218, v176, 2, s16
	ds_read_b128 v[178:181], v218
	ds_read_b128 v[182:185], v218 offset:64
	ds_read_b128 v[186:189], v218 offset:128
	ds_read_b128 v[190:193], v218 offset:192
	ds_read_b128 v[194:197], v218 offset:512
	ds_read_b128 v[198:201], v218 offset:576
	ds_read_b128 v[202:205], v218 offset:640
	ds_read_b128 v[206:209], v218 offset:704
	v_mov_b32_e32 v214, 0xbfb8aa3b
	v_mov_b32_e32 v215, 0xbfb8aa3b
	v_mov_b32_e32 v216, 1.0
	v_mov_b32_e32 v217, 1.0
	s_lshl_b32 s17, s41, 7
	s_mul_hi_i32 s15, s14, 0xb40
	s_mulk_i32 s14, 0xb40
	s_ashr_i32 s18, s17, 31
	s_add_u32 s14, s14, s17
	s_addc_u32 s15, s15, s18
	s_lshl_b64 s[14:15], s[14:15], 1
	s_add_u32 s14, s35, s14
	s_addc_u32 s15, s36, s15
	s_waitcnt lgkmcnt(0)
	v_pk_mul_f32 v[118:119], v[118:119], v[178:179]
	v_pk_mul_f32 v[120:121], v[120:121], v[180:181]
	v_pk_mul_f32 v[174:175], v[214:215], v[118:119]
	v_pk_mul_f32 v[176:177], v[214:215], v[120:121]
	v_exp_f32_e32 v174, v174
	v_exp_f32_e32 v175, v175
	v_exp_f32_e32 v176, v176
	v_exp_f32_e32 v177, v177
	v_pk_mul_f32 v[114:115], v[114:115], v[178:179]
	v_pk_mul_f32 v[116:117], v[116:117], v[180:181]
	v_pk_add_f32 v[174:175], v[216:217], v[174:175]
	v_pk_add_f32 v[176:177], v[216:217], v[176:177]
	v_rcp_f32_e32 v174, v174
	v_rcp_f32_e32 v175, v175
	v_rcp_f32_e32 v176, v176
	v_rcp_f32_e32 v177, v177
	v_pk_mul_f32 v[118:119], v[118:119], v[174:175]
	v_pk_mul_f32 v[120:121], v[120:121], v[176:177]
	v_pk_mul_f32 v[114:115], v[114:115], v[118:119]
	v_pk_mul_f32 v[116:117], v[116:117], v[120:121]
	v_cvt_pk_bf16_f32 v114, v114, v115
	v_cvt_pk_bf16_f32 v115, v116, v117
	global_store_short v210, v114, s[14:15]
	global_store_short_d16_hi v211, v114, s[14:15]
	global_store_short v212, v115, s[14:15]
	global_store_short_d16_hi v213, v115, s[14:15]
	v_pk_mul_f32 v[126:127], v[126:127], v[178:179]
	v_pk_mul_f32 v[128:129], v[128:129], v[180:181]
	v_pk_mul_f32 v[174:175], v[214:215], v[126:127]
	v_pk_mul_f32 v[176:177], v[214:215], v[128:129]
	v_exp_f32_e32 v174, v174
	v_exp_f32_e32 v175, v175
	v_exp_f32_e32 v176, v176
	v_exp_f32_e32 v177, v177
	v_pk_mul_f32 v[122:123], v[122:123], v[178:179]
	v_pk_mul_f32 v[124:125], v[124:125], v[180:181]
	v_pk_add_f32 v[174:175], v[216:217], v[174:175]
	v_pk_add_f32 v[176:177], v[216:217], v[176:177]
	v_rcp_f32_e32 v174, v174
	v_rcp_f32_e32 v175, v175
	v_rcp_f32_e32 v176, v176
	v_rcp_f32_e32 v177, v177
	v_pk_mul_f32 v[126:127], v[126:127], v[174:175]
	v_pk_mul_f32 v[128:129], v[128:129], v[176:177]
	v_pk_mul_f32 v[122:123], v[122:123], v[126:127]
	v_pk_mul_f32 v[124:125], v[124:125], v[128:129]
	v_cvt_pk_bf16_f32 v122, v122, v123
	v_cvt_pk_bf16_f32 v123, v124, v125
	global_store_short v210, v122, s[14:15] offset:128
	global_store_short_d16_hi v211, v122, s[14:15] offset:128
	global_store_short v212, v123, s[14:15] offset:128
	global_store_short_d16_hi v213, v123, s[14:15] offset:128
	s_add_u32 s14, s14, 0x16800
	s_addc_u32 s15, s15, 0
	v_pk_mul_f32 v[102:103], v[102:103], v[182:183]
	v_pk_mul_f32 v[104:105], v[104:105], v[184:185]
	v_pk_mul_f32 v[174:175], v[214:215], v[102:103]
	v_pk_mul_f32 v[176:177], v[214:215], v[104:105]
	v_exp_f32_e32 v174, v174
	v_exp_f32_e32 v175, v175
	v_exp_f32_e32 v176, v176
	v_exp_f32_e32 v177, v177
	v_pk_mul_f32 v[98:99], v[98:99], v[182:183]
	v_pk_mul_f32 v[100:101], v[100:101], v[184:185]
	v_pk_add_f32 v[174:175], v[216:217], v[174:175]
	v_pk_add_f32 v[176:177], v[216:217], v[176:177]
	v_rcp_f32_e32 v174, v174
	v_rcp_f32_e32 v175, v175
	v_rcp_f32_e32 v176, v176
	v_rcp_f32_e32 v177, v177
	v_pk_mul_f32 v[102:103], v[102:103], v[174:175]
	v_pk_mul_f32 v[104:105], v[104:105], v[176:177]
	v_pk_mul_f32 v[98:99], v[98:99], v[102:103]
	v_pk_mul_f32 v[100:101], v[100:101], v[104:105]
	v_cvt_pk_bf16_f32 v98, v98, v99
	v_cvt_pk_bf16_f32 v99, v100, v101
	global_store_short v210, v98, s[14:15]
	global_store_short_d16_hi v211, v98, s[14:15]
	global_store_short v212, v99, s[14:15]
	global_store_short_d16_hi v213, v99, s[14:15]
	v_pk_mul_f32 v[110:111], v[110:111], v[182:183]
	v_pk_mul_f32 v[112:113], v[112:113], v[184:185]
	v_pk_mul_f32 v[174:175], v[214:215], v[110:111]
	v_pk_mul_f32 v[176:177], v[214:215], v[112:113]
	v_exp_f32_e32 v174, v174
	v_exp_f32_e32 v175, v175
	v_exp_f32_e32 v176, v176
	v_exp_f32_e32 v177, v177
	v_pk_mul_f32 v[106:107], v[106:107], v[182:183]
	v_pk_mul_f32 v[108:109], v[108:109], v[184:185]
	v_pk_add_f32 v[174:175], v[216:217], v[174:175]
	v_pk_add_f32 v[176:177], v[216:217], v[176:177]
	v_rcp_f32_e32 v174, v174
	v_rcp_f32_e32 v175, v175
	v_rcp_f32_e32 v176, v176
	v_rcp_f32_e32 v177, v177
	v_pk_mul_f32 v[110:111], v[110:111], v[174:175]
	v_pk_mul_f32 v[112:113], v[112:113], v[176:177]
	v_pk_mul_f32 v[106:107], v[106:107], v[110:111]
	v_pk_mul_f32 v[108:109], v[108:109], v[112:113]
	v_cvt_pk_bf16_f32 v106, v106, v107
	v_cvt_pk_bf16_f32 v107, v108, v109
	global_store_short v210, v106, s[14:15] offset:128
	global_store_short_d16_hi v211, v106, s[14:15] offset:128
	global_store_short v212, v107, s[14:15] offset:128
	global_store_short_d16_hi v213, v107, s[14:15] offset:128
	s_add_u32 s14, s14, 0x16800
; #define GAS __attribute__((address_space(1)))
; __device__ __forceinline__ unsigned f2bf(float f) { return pk2(f, f) & 0xffffu; }
; __device__ __forceinline__ float sigmoidf_(float v) { return __builtin_amdgcn_rcpf(1.f + __builtin_amdgcn_exp2f(-LOG2E * v)); }
; __device__ __forceinline__ void load_rr(const GAS float* ssq, int brow, int par) {
;     ...
;   if (tx < 256) {
;     const GAS f32x4* s = (const GAS f32x4*)(ssq + (size_t)(brow + tx) * 16);
;     f32x4 a = s[0], b = s[1], c = s[2], d = s[3];
;     float t = ((a.x + a.y) + (a.z + a.w)) + ((b.x + b.y) + (b.z + b.w)) + ((c.x + c.y) + (c.z + c.w)) + ((d.x + d.y) + (d.z + d.w));
;     rr[tx] = rsqrtf(t * (1.f / DM) + EPS);
;   }
; __device__ __forceinline__ void phase_up(int pass) {
;     ...
;         for (int j = 0; j < 4; ++j) {
;           const int rowl = ai * 128 + wr * 64 + m * 16 + fq * 4 + j;
;           const float r = rr[rowl];
; #pragma unroll
;           for (int bj = 0; bj < 2; ++bj) {
;             const float g = acc[ai][bj][m][0][j] * r, u = acc[ai][bj][m][1][j] * r;
;             const float v = g * sigmoidf_(g) * u;
;             *(GAS unsigned short*)(tb + (off0 + (unsigned)(((ai * 128 + m * 16 + j) * FFP + bj * 64) * 2))) = (unsigned short)f2bf(v);
;           }
;         }
	s_addc_u32 s15, s15, 0
	v_pk_mul_f32 v[86:87], v[86:87], v[186:187]
	v_pk_mul_f32 v[88:89], v[88:89], v[188:189]
	v_pk_mul_f32 v[174:175], v[214:215], v[86:87]
	v_pk_mul_f32 v[176:177], v[214:215], v[88:89]
	v_exp_f32_e32 v174, v174
	v_exp_f32_e32 v175, v175
	v_exp_f32_e32 v176, v176
	v_exp_f32_e32 v177, v177
	v_pk_mul_f32 v[82:83], v[82:83], v[186:187]
	v_pk_mul_f32 v[84:85], v[84:85], v[188:189]
	v_pk_add_f32 v[174:175], v[216:217], v[174:175]
	v_pk_add_f32 v[176:177], v[216:217], v[176:177]
	v_rcp_f32_e32 v174, v174
	v_rcp_f32_e32 v175, v175
	v_rcp_f32_e32 v176, v176
	v_rcp_f32_e32 v177, v177
	v_pk_mul_f32 v[86:87], v[86:87], v[174:175]
	v_pk_mul_f32 v[88:89], v[88:89], v[176:177]
	v_pk_mul_f32 v[82:83], v[82:83], v[86:87]
	v_pk_mul_f32 v[84:85], v[84:85], v[88:89]
	v_cvt_pk_bf16_f32 v82, v82, v83
	v_cvt_pk_bf16_f32 v83, v84, v85
	global_store_short v210, v82, s[14:15]
	global_store_short_d16_hi v211, v82, s[14:15]
	global_store_short v212, v83, s[14:15]
	global_store_short_d16_hi v213, v83, s[14:15]
	v_pk_mul_f32 v[94:95], v[94:95], v[186:187]
	v_pk_mul_f32 v[96:97], v[96:97], v[188:189]
	v_pk_mul_f32 v[174:175], v[214:215], v[94:95]
	v_pk_mul_f32 v[176:177], v[214:215], v[96:97]
	v_exp_f32_e32 v174, v174
	v_exp_f32_e32 v175, v175
	v_exp_f32_e32 v176, v176
	v_exp_f32_e32 v177, v177
	v_pk_mul_f32 v[90:91], v[90:91], v[186:187]
	v_pk_mul_f32 v[92:93], v[92:93], v[188:189]
	v_pk_add_f32 v[174:175], v[216:217], v[174:175]
	v_pk_add_f32 v[176:177], v[216:217], v[176:177]
	v_rcp_f32_e32 v174, v174
	v_rcp_f32_e32 v175, v175
	v_rcp_f32_e32 v176, v176
	v_rcp_f32_e32 v177, v177
	v_pk_mul_f32 v[94:95], v[94:95], v[174:175]
	v_pk_mul_f32 v[96:97], v[96:97], v[176:177]
	v_pk_mul_f32 v[90:91], v[90:91], v[94:95]
	v_pk_mul_f32 v[92:93], v[92:93], v[96:97]
	v_cvt_pk_bf16_f32 v90, v90, v91
	v_cvt_pk_bf16_f32 v91, v92, v93
	global_store_short v210, v90, s[14:15] offset:128
	global_store_short_d16_hi v211, v90, s[14:15] offset:128
	global_store_short v212, v91, s[14:15] offset:128
	global_store_short_d16_hi v213, v91, s[14:15] offset:128
	s_add_u32 s14, s14, 0x16800
	s_addc_u32 s15, s15, 0
	v_pk_mul_f32 v[70:71], v[70:71], v[190:191]
	v_pk_mul_f32 v[72:73], v[72:73], v[192:193]
	v_pk_mul_f32 v[174:175], v[214:215], v[70:71]
	v_pk_mul_f32 v[176:177], v[214:215], v[72:73]
	v_exp_f32_e32 v174, v174
	v_exp_f32_e32 v175, v175
	v_exp_f32_e32 v176, v176
	v_exp_f32_e32 v177, v177
	v_pk_mul_f32 v[66:67], v[66:67], v[190:191]
	v_pk_mul_f32 v[68:69], v[68:69], v[192:193]
	v_pk_add_f32 v[174:175], v[216:217], v[174:175]
	v_pk_add_f32 v[176:177], v[216:217], v[176:177]
	v_rcp_f32_e32 v174, v174
	v_rcp_f32_e32 v175, v175
	v_rcp_f32_e32 v176, v176
	v_rcp_f32_e32 v177, v177
	v_pk_mul_f32 v[70:71], v[70:71], v[174:175]
	v_pk_mul_f32 v[72:73], v[72:73], v[176:177]
	v_pk_mul_f32 v[66:67], v[66:67], v[70:71]
	v_pk_mul_f32 v[68:69], v[68:69], v[72:73]
	v_cvt_pk_bf16_f32 v66, v66, v67
	v_cvt_pk_bf16_f32 v67, v68, v69
	global_store_short v210, v66, s[14:15]
	global_store_short_d16_hi v211, v66, s[14:15]
	global_store_short v212, v67, s[14:15]
	global_store_short_d16_hi v213, v67, s[14:15]
	v_pk_mul_f32 v[78:79], v[78:79], v[190:191]
	v_pk_mul_f32 v[80:81], v[80:81], v[192:193]
	v_pk_mul_f32 v[174:175], v[214:215], v[78:79]
	v_pk_mul_f32 v[176:177], v[214:215], v[80:81]
	v_exp_f32_e32 v174, v174
	v_exp_f32_e32 v175, v175
	v_exp_f32_e32 v176, v176
	v_exp_f32_e32 v177, v177
	v_pk_mul_f32 v[74:75], v[74:75], v[190:191]
	v_pk_mul_f32 v[76:77], v[76:77], v[192:193]
	v_pk_add_f32 v[174:175], v[216:217], v[174:175]
	v_pk_add_f32 v[176:177], v[216:217], v[176:177]
	v_rcp_f32_e32 v174, v174
	v_rcp_f32_e32 v175, v175
	v_rcp_f32_e32 v176, v176
	v_rcp_f32_e32 v177, v177
	v_pk_mul_f32 v[78:79], v[78:79], v[174:175]
	v_pk_mul_f32 v[80:81], v[80:81], v[176:177]
	v_pk_mul_f32 v[74:75], v[74:75], v[78:79]
	v_pk_mul_f32 v[76:77], v[76:77], v[80:81]
	v_cvt_pk_bf16_f32 v74, v74, v75
	v_cvt_pk_bf16_f32 v75, v76, v77
	global_store_short v210, v74, s[14:15] offset:128
	global_store_short_d16_hi v211, v74, s[14:15] offset:128
	global_store_short v212, v75, s[14:15] offset:128
	global_store_short_d16_hi v213, v75, s[14:15] offset:128
	s_and_b64 vcc, exec, s[12:13]
	s_cbranch_vccnz .Lup1_rr_skip
	v_cmp_gt_i32_e32 vcc, s34, v170
	s_and_saveexec_b64 s[18:19], vcc
	s_cbranch_execz .Lup1_rr_done
	s_lshl_b32 s17, s37, 10
	s_xor_b32 s17, s17, 0x400
	s_addk_i32 s17, 0x100
	v_lshl_add_u32 v130, v170, 2, s17
	v_add_u32_e32 v130, 0x20000, v130
	s_waitcnt vmcnt(32)
	v_mov_b32_e32 v132, v137
	v_mov_b32_e32 v133, v138
	v_mov_b32_e32 v137, v139
	v_mov_b32_e32 v138, v141
	v_mov_b32_e32 v139, v142
	v_mov_b32_e32 v141, v143
	v_pk_add_f32 v[132:133], v[132:133], v[136:137]
	v_pk_add_f32 v[136:137], v[138:139], v[140:141]
	v_pk_add_f32 v[132:133], v[132:133], v[132:133] op_sel:[0,1] op_sel_hi:[1,0]
	v_pk_add_f32 v[136:137], v[136:137], v[136:137] op_sel:[0,1] op_sel_hi:[1,0]
	v_add_f32_e32 v142, v144, v145
	v_add_f32_e32 v144, v146, v147
	v_mov_b32_e32 v143, v150
	v_mov_b32_e32 v145, v151
	v_mov_b32_e32 v133, v148
	v_mov_b32_e32 v137, v149
	v_pk_add_f32 v[138:139], v[142:143], v[144:145]
	v_pk_add_f32 v[132:133], v[132:133], v[136:137]
	s_nop 0
	v_pk_add_f32 v[132:133], v[132:133], v[138:139]
	s_nop 0
	v_add_f32_e32 v132, v132, v133
	v_fmamk_f32 v132, v132, 0x3a800000, v134
	v_mul_f32_e32 v133, 0x4b800000, v132
	v_cmp_gt_f32_e32 vcc, s39, v132
	s_nop 1
	v_cndmask_b32_e32 v132, v132, v133, vcc
	v_rsq_f32_e32 v132, v132
	s_nop 0
	v_mul_f32_e32 v133, 0x45800000, v132
	v_cndmask_b32_e32 v132, v132, v133, vcc
	ds_write_b32 v130, v132

; #define GAS __attribute__((address_space(1)))
; __device__ __forceinline__ unsigned f2bf(float f) { return pk2(f, f) & 0xffffu; }
; __device__ __forceinline__ float sigmoidf_(float v) { return __builtin_amdgcn_rcpf(1.f + __builtin_amdgcn_exp2f(-LOG2E * v)); }
; __device__ __forceinline__ void phase_up(int pass) {
;     ...
;         for (int j = 0; j < 4; ++j) {
;           const int rowl = ai * 128 + wr * 64 + m * 16 + fq * 4 + j;
;           const float r = rr[rowl];
; #pragma unroll
;           for (int bj = 0; bj < 2; ++bj) {
;             const float g = acc[ai][bj][m][0][j] * r, u = acc[ai][bj][m][1][j] * r;
;             const float v = g * sigmoidf_(g) * u;
;             *(GAS unsigned short*)(tb + (off0 + (unsigned)(((ai * 128 + m * 16 + j) * FFP + bj * 64) * 2))) = (unsigned short)f2bf(v);
;           }
;         }
.Lup1_rr_skip:
	s_add_u32 s14, s14, 0x70800
	s_addc_u32 s15, s15, 0
	v_pk_mul_f32 v[54:55], v[54:55], v[194:195]
	v_pk_mul_f32 v[56:57], v[56:57], v[196:197]
	v_pk_mul_f32 v[174:175], v[214:215], v[54:55]
	v_pk_mul_f32 v[176:177], v[214:215], v[56:57]
	v_exp_f32_e32 v174, v174
	v_exp_f32_e32 v175, v175
	v_exp_f32_e32 v176, v176
	v_exp_f32_e32 v177, v177
	v_pk_mul_f32 v[50:51], v[50:51], v[194:195]
	v_pk_mul_f32 v[52:53], v[52:53], v[196:197]
	v_pk_add_f32 v[174:175], v[216:217], v[174:175]
	v_pk_add_f32 v[176:177], v[216:217], v[176:177]
	v_rcp_f32_e32 v174, v174
	v_rcp_f32_e32 v175, v175
	v_rcp_f32_e32 v176, v176
	v_rcp_f32_e32 v177, v177
	v_pk_mul_f32 v[54:55], v[54:55], v[174:175]
	v_pk_mul_f32 v[56:57], v[56:57], v[176:177]
	v_pk_mul_f32 v[50:51], v[50:51], v[54:55]
	v_pk_mul_f32 v[52:53], v[52:53], v[56:57]
	v_cvt_pk_bf16_f32 v50, v50, v51
	v_cvt_pk_bf16_f32 v51, v52, v53
	global_store_short v210, v50, s[14:15]
	global_store_short_d16_hi v211, v50, s[14:15]
	global_store_short v212, v51, s[14:15]
	global_store_short_d16_hi v213, v51, s[14:15]
	v_pk_mul_f32 v[62:63], v[62:63], v[194:195]
	v_pk_mul_f32 v[64:65], v[64:65], v[196:197]
	v_pk_mul_f32 v[174:175], v[214:215], v[62:63]
	v_pk_mul_f32 v[176:177], v[214:215], v[64:65]
	v_exp_f32_e32 v174, v174
	v_exp_f32_e32 v175, v175
	v_exp_f32_e32 v176, v176
	v_exp_f32_e32 v177, v177
	v_pk_mul_f32 v[58:59], v[58:59], v[194:195]
	v_pk_mul_f32 v[60:61], v[60:61], v[196:197]
	v_pk_add_f32 v[174:175], v[216:217], v[174:175]
	v_pk_add_f32 v[176:177], v[216:217], v[176:177]
	v_rcp_f32_e32 v174, v174
	v_rcp_f32_e32 v175, v175
	v_rcp_f32_e32 v176, v176
	v_rcp_f32_e32 v177, v177
	v_pk_mul_f32 v[62:63], v[62:63], v[174:175]
	v_pk_mul_f32 v[64:65], v[64:65], v[176:177]
	v_pk_mul_f32 v[58:59], v[58:59], v[62:63]
	v_pk_mul_f32 v[60:61], v[60:61], v[64:65]
	v_cvt_pk_bf16_f32 v58, v58, v59
	v_cvt_pk_bf16_f32 v59, v60, v61
	global_store_short v210, v58, s[14:15] offset:128
	global_store_short_d16_hi v211, v58, s[14:15] offset:128
	global_store_short v212, v59, s[14:15] offset:128
	global_store_short_d16_hi v213, v59, s[14:15] offset:128
	s_add_u32 s14, s14, 0x16800
	s_addc_u32 s15, s15, 0
	v_pk_mul_f32 v[42:43], v[42:43], v[198:199]
	v_pk_mul_f32 v[44:45], v[44:45], v[200:201]
	v_pk_mul_f32 v[174:175], v[214:215], v[42:43]
	v_pk_mul_f32 v[176:177], v[214:215], v[44:45]
	v_exp_f32_e32 v174, v174
	v_exp_f32_e32 v175, v175
	v_exp_f32_e32 v176, v176
	v_exp_f32_e32 v177, v177
	v_pk_mul_f32 v[34:35], v[34:35], v[198:199]
	v_pk_mul_f32 v[36:37], v[36:37], v[200:201]
	v_pk_add_f32 v[174:175], v[216:217], v[174:175]
	v_pk_add_f32 v[176:177], v[216:217], v[176:177]
	v_rcp_f32_e32 v174, v174
	v_rcp_f32_e32 v175, v175
	v_rcp_f32_e32 v176, v176
	v_rcp_f32_e32 v177, v177
	v_pk_mul_f32 v[42:43], v[42:43], v[174:175]
	v_pk_mul_f32 v[44:45], v[44:45], v[176:177]
	v_pk_mul_f32 v[34:35], v[34:35], v[42:43]
	v_pk_mul_f32 v[36:37], v[36:37], v[44:45]
	v_cvt_pk_bf16_f32 v34, v34, v35
	v_cvt_pk_bf16_f32 v35, v36, v37
	global_store_short v210, v34, s[14:15]
	global_store_short_d16_hi v211, v34, s[14:15]
	global_store_short v212, v35, s[14:15]
	global_store_short_d16_hi v213, v35, s[14:15]
	v_pk_mul_f32 v[46:47], v[46:47], v[198:199]
	v_pk_mul_f32 v[48:49], v[48:49], v[200:201]
	v_pk_mul_f32 v[174:175], v[214:215], v[46:47]
	v_pk_mul_f32 v[176:177], v[214:215], v[48:49]
	v_exp_f32_e32 v174, v174
	v_exp_f32_e32 v175, v175
	v_exp_f32_e32 v176, v176
	v_exp_f32_e32 v177, v177
	v_pk_mul_f32 v[38:39], v[38:39], v[198:199]
	v_pk_mul_f32 v[40:41], v[40:41], v[200:201]
	v_pk_add_f32 v[174:175], v[216:217], v[174:175]
	v_pk_add_f32 v[176:177], v[216:217], v[176:177]
	v_rcp_f32_e32 v174, v174
	v_rcp_f32_e32 v175, v175
	v_rcp_f32_e32 v176, v176
	v_rcp_f32_e32 v177, v177
	v_pk_mul_f32 v[46:47], v[46:47], v[174:175]
	v_pk_mul_f32 v[48:49], v[48:49], v[176:177]
	v_pk_mul_f32 v[38:39], v[38:39], v[46:47]
	v_pk_mul_f32 v[40:41], v[40:41], v[48:49]
	v_cvt_pk_bf16_f32 v38, v38, v39
	v_cvt_pk_bf16_f32 v39, v40, v41
	global_store_short v210, v38, s[14:15] offset:128
	global_store_short_d16_hi v211, v38, s[14:15] offset:128
	global_store_short v212, v39, s[14:15] offset:128
	global_store_short_d16_hi v213, v39, s[14:15] offset:128
	s_add_u32 s14, s14, 0x16800
; #define GAS __attribute__((address_space(1)))
; __device__ __forceinline__ unsigned f2bf(float f) { return pk2(f, f) & 0xffffu; }
; __device__ __forceinline__ float sigmoidf_(float v) { return __builtin_amdgcn_rcpf(1.f + __builtin_amdgcn_exp2f(-LOG2E * v)); }
; __device__ __forceinline__ void phase_up(int pass) {
;     ...
;         for (int j = 0; j < 4; ++j) {
;           const int rowl = ai * 128 + wr * 64 + m * 16 + fq * 4 + j;
;           const float r = rr[rowl];
; #pragma unroll
;           for (int bj = 0; bj < 2; ++bj) {
;             const float g = acc[ai][bj][m][0][j] * r, u = acc[ai][bj][m][1][j] * r;
;             const float v = g * sigmoidf_(g) * u;
;             *(GAS unsigned short*)(tb + (off0 + (unsigned)(((ai * 128 + m * 16 + j) * FFP + bj * 64) * 2))) = (unsigned short)f2bf(v);
;           }
;         }
;     par ^= 1;
	s_addc_u32 s15, s15, 0
	v_pk_mul_f32 v[22:23], v[22:23], v[202:203]
	v_pk_mul_f32 v[24:25], v[24:25], v[204:205]
	v_pk_mul_f32 v[174:175], v[214:215], v[22:23]
	v_pk_mul_f32 v[176:177], v[214:215], v[24:25]
	v_exp_f32_e32 v174, v174
	v_exp_f32_e32 v175, v175
	v_exp_f32_e32 v176, v176
	v_exp_f32_e32 v177, v177
	v_pk_mul_f32 v[18:19], v[18:19], v[202:203]
	v_pk_mul_f32 v[20:21], v[20:21], v[204:205]
	v_pk_add_f32 v[174:175], v[216:217], v[174:175]
	v_pk_add_f32 v[176:177], v[216:217], v[176:177]
	v_rcp_f32_e32 v174, v174
	v_rcp_f32_e32 v175, v175
	v_rcp_f32_e32 v176, v176
	v_rcp_f32_e32 v177, v177
	v_pk_mul_f32 v[22:23], v[22:23], v[174:175]
	v_pk_mul_f32 v[24:25], v[24:25], v[176:177]
	v_pk_mul_f32 v[18:19], v[18:19], v[22:23]
	v_pk_mul_f32 v[20:21], v[20:21], v[24:25]
	v_cvt_pk_bf16_f32 v18, v18, v19
	v_cvt_pk_bf16_f32 v19, v20, v21
	global_store_short v210, v18, s[14:15]
	global_store_short_d16_hi v211, v18, s[14:15]
	global_store_short v212, v19, s[14:15]
	global_store_short_d16_hi v213, v19, s[14:15]
	v_pk_mul_f32 v[30:31], v[30:31], v[202:203]
	v_pk_mul_f32 v[32:33], v[32:33], v[204:205]
	v_pk_mul_f32 v[174:175], v[214:215], v[30:31]
	v_pk_mul_f32 v[176:177], v[214:215], v[32:33]
	v_exp_f32_e32 v174, v174
	v_exp_f32_e32 v175, v175
	v_exp_f32_e32 v176, v176
	v_exp_f32_e32 v177, v177
	v_pk_mul_f32 v[26:27], v[26:27], v[202:203]
	v_pk_mul_f32 v[28:29], v[28:29], v[204:205]
	v_pk_add_f32 v[174:175], v[216:217], v[174:175]
	v_pk_add_f32 v[176:177], v[216:217], v[176:177]
	v_rcp_f32_e32 v174, v174
	v_rcp_f32_e32 v175, v175
	v_rcp_f32_e32 v176, v176
	v_rcp_f32_e32 v177, v177
	v_pk_mul_f32 v[30:31], v[30:31], v[174:175]
	v_pk_mul_f32 v[32:33], v[32:33], v[176:177]
	v_pk_mul_f32 v[26:27], v[26:27], v[30:31]
	v_pk_mul_f32 v[28:29], v[28:29], v[32:33]
	v_cvt_pk_bf16_f32 v26, v26, v27
	v_cvt_pk_bf16_f32 v27, v28, v29
	global_store_short v210, v26, s[14:15] offset:128
	global_store_short_d16_hi v211, v26, s[14:15] offset:128
	global_store_short v212, v27, s[14:15] offset:128
	global_store_short_d16_hi v213, v27, s[14:15] offset:128
	s_add_u32 s14, s14, 0x16800
	s_addc_u32 s15, s15, 0
	v_pk_mul_f32 v[10:11], v[10:11], v[206:207]
	v_pk_mul_f32 v[12:13], v[12:13], v[208:209]
	v_pk_mul_f32 v[174:175], v[214:215], v[10:11]
	v_pk_mul_f32 v[176:177], v[214:215], v[12:13]
	v_exp_f32_e32 v174, v174
	v_exp_f32_e32 v175, v175
	v_exp_f32_e32 v176, v176
	v_exp_f32_e32 v177, v177
	v_pk_mul_f32 v[2:3], v[2:3], v[206:207]
	v_pk_mul_f32 v[4:5], v[4:5], v[208:209]
	v_pk_add_f32 v[174:175], v[216:217], v[174:175]
	v_pk_add_f32 v[176:177], v[216:217], v[176:177]
	v_rcp_f32_e32 v174, v174
	v_rcp_f32_e32 v175, v175
	v_rcp_f32_e32 v176, v176
	v_rcp_f32_e32 v177, v177
	v_pk_mul_f32 v[10:11], v[10:11], v[174:175]
	v_pk_mul_f32 v[12:13], v[12:13], v[176:177]
	v_pk_mul_f32 v[2:3], v[2:3], v[10:11]
	v_pk_mul_f32 v[4:5], v[4:5], v[12:13]
	v_cvt_pk_bf16_f32 v2, v2, v3
	v_cvt_pk_bf16_f32 v3, v4, v5
	global_store_short v210, v2, s[14:15]
	global_store_short_d16_hi v211, v2, s[14:15]
	global_store_short v212, v3, s[14:15]
	global_store_short_d16_hi v213, v3, s[14:15]
	v_pk_mul_f32 v[14:15], v[14:15], v[206:207]
	v_pk_mul_f32 v[16:17], v[16:17], v[208:209]
	v_pk_mul_f32 v[174:175], v[214:215], v[14:15]
	v_pk_mul_f32 v[176:177], v[214:215], v[16:17]
	v_exp_f32_e32 v174, v174
	v_exp_f32_e32 v175, v175
	v_exp_f32_e32 v176, v176
	v_exp_f32_e32 v177, v177
	v_pk_mul_f32 v[6:7], v[6:7], v[206:207]
	v_pk_mul_f32 v[8:9], v[8:9], v[208:209]
	v_pk_add_f32 v[174:175], v[216:217], v[174:175]
	v_pk_add_f32 v[176:177], v[216:217], v[176:177]
	v_rcp_f32_e32 v174, v174
	v_rcp_f32_e32 v175, v175
	v_rcp_f32_e32 v176, v176
	v_rcp_f32_e32 v177, v177
	v_pk_mul_f32 v[14:15], v[14:15], v[174:175]
	v_pk_mul_f32 v[16:17], v[16:17], v[176:177]
	v_pk_mul_f32 v[6:7], v[6:7], v[14:15]
	v_pk_mul_f32 v[8:9], v[8:9], v[16:17]
	v_cvt_pk_bf16_f32 v6, v6, v7
	v_cvt_pk_bf16_f32 v7, v8, v9
	global_store_short v210, v6, s[14:15] offset:128
	global_store_short_d16_hi v211, v6, s[14:15] offset:128
	global_store_short v212, v7, s[14:15] offset:128
	global_store_short_d16_hi v213, v7, s[14:15] offset:128
	s_xor_b32 s37, s37, 1
	s_andn2_b64 vcc, exec, s[12:13]
	s_mov_b32 s41, s20
	s_cbranch_vccz .LBB0_890
